# x1rows: all sixteen per-row loads (mix, g_post, gate1, x) issued up front with counted waits
# speedup vs baseline: 1.0056x; 1.0056x over previous
; __device__ __forceinline__ float dot4(f32x4 a) { return (a[0] * a[0] + a[1] * a[1]) + (a[2] * a[2] + a[3] * a[3]); }
; __device__ __forceinline__ void ph_x1rows(int tbase) {
;     ...
;     for (int m = gw; m < TG; m += NGW) { const int t = tbase + m, b = t >> 12;
;         float sv = lane < 16 ? SSQ_MIX[lane * TT + t] : 0.f; sv += __shfl_xor(sv, 1); sv += __shfl_xor(sv, 2); sv += __shfl_xor(sv, 4); sv += __shfl_xor(sv, 8); sv = __shfl(sv, 0);
;         const float rs1 = rsqrtf(sv * (1.f / 1024.f) + EPS); const float* mod = MOD + b * 6144;
;         f32x4 v[4]; float s = 0.f;
; #pragma unroll
;         for (int j = 0; j < 4; ++j) { const int c0 = 4 * lane + 256 * j; const u32x2 w = *(const u32x2*)(MIX + (size_t)m * 1024 + c0);
;             const f32x4 f = {bflo(w.x), bfhi(w.x), bflo(w.y), bfhi(w.y)}; const f32x4 g = *(const f32x4*)(g_post_mix + c0), ga = *(const f32x4*)(mod + 2048 + c0);
;             v[j] = *(const f32x4*)(x + (size_t)t * 1024 + c0) + ga * (f * rs1 * g); *(f32x4*)(out + (size_t)t * 1024 + c0) = v[j]; s += dot4(v[j]); }
.LBB0_1217:
	s_or_b64 exec, exec, s[8:9]
	s_waitcnt vmcnt(0)
	ds_bpermute_b32 v2, v30, v0
	s_add_i32 s10, s63, s4
	s_ashr_i32 s2, s10, 12
	s_mul_i32 s8, s2, 0x1800
	s_ashr_i32 s9, s8, 31
	s_waitcnt lgkmcnt(0)
	v_add_f32_e32 v0, v0, v2
	ds_bpermute_b32 v2, v31, v0
	s_lshl_b64 s[8:9], s[8:9], 2
	s_add_u32 s5, s12, s8
	s_addc_u32 s7, s13, s9
	s_add_u32 s8, s5, 0x2000
	s_waitcnt lgkmcnt(0)
	v_add_f32_e32 v0, v0, v2
	ds_bpermute_b32 v2, v32, v0
	s_addc_u32 s9, s7, 0
	s_ashr_i32 s11, s10, 31
	s_lshl_b64 s[10:11], s[10:11], 12
	v_lshl_add_u64 v[6:7], v[22:23], 0, s[10:11]
	s_waitcnt lgkmcnt(0)
	v_add_f32_e32 v0, v0, v2
	ds_bpermute_b32 v2, v33, v0
	s_add_u32 s64, s5, 0x4000
	s_addc_u32 s65, s7, 0
	s_add_u32 s72, s5, 0x3000
	s_addc_u32 s73, s7, 0
	s_waitcnt lgkmcnt(0)
	v_add_f32_e32 v0, v0, v2
	ds_bpermute_b32 v0, v244, v0
	s_mov_b32 s2, 0xe7c00000
	s_add_i32 s4, s4, s6
	s_cmpk_lt_i32 s4, 0x4000
	s_waitcnt lgkmcnt(0)
	v_fmamk_f32 v0, v0, 0x3a800000, v220
	v_cmp_gt_f32_e64 s[38:39], s51, v0
	v_mul_f32_e32 v2, 0x4b800000, v0
	s_nop 0
	v_cndmask_b32_e64 v0, v0, v2, s[38:39]
	v_rsq_f32_e32 v0, v0
	s_nop 0
	v_mul_f32_e32 v2, 0x45800000, v0
	v_cndmask_b32_e64 v0, v0, v2, s[38:39]
	global_load_dwordx2 v[144:145], v[26:27], off
	global_load_dwordx2 v[146:147], v[26:27], off offset:512
	global_load_dwordx2 v[148:149], v[26:27], off offset:1024
	global_load_dwordx2 v[150:151], v[26:27], off offset:1536
	global_load_dwordx4 v[152:155], v[20:21], off
	global_load_dwordx4 v[168:171], v37, s[8:9]
	global_load_dwordx4 v[184:187], v[6:7], off
	global_load_dwordx4 v[156:159], v[20:21], off offset:1024
	global_load_dwordx4 v[172:175], v38, s[8:9]
	global_load_dwordx4 v[188:191], v[6:7], off offset:1024
	global_load_dwordx4 v[160:163], v[20:21], off offset:2048
	global_load_dwordx4 v[176:179], v39, s[8:9]
	global_load_dwordx4 v[192:195], v[6:7], off offset:2048
	global_load_dwordx4 v[164:167], v[20:21], off offset:3072
	global_load_dwordx4 v[180:183], v40, s[8:9]
	global_load_dwordx4 v[196:199], v[6:7], off offset:3072
	s_waitcnt vmcnt(12)
	v_lshlrev_b32_e32 v16, 16, v144
	v_and_b32_e32 v17, 0xffff0000, v144
	v_lshlrev_b32_e32 v28, 16, v145
	v_and_b32_e32 v29, 0xffff0000, v145
	v_pk_mul_f32 v[28:29], v[0:1], v[28:29] op_sel_hi:[0,1]
	v_pk_mul_f32 v[16:17], v[0:1], v[16:17] op_sel_hi:[0,1]
	s_waitcnt vmcnt(11)
	v_pk_mul_f32 v[2:3], v[152:153], v[16:17]
	v_pk_mul_f32 v[4:5], v[154:155], v[28:29]
	v_lshl_add_u64 v[28:29], v[24:25], 0, s[10:11]
	s_waitcnt vmcnt(9)
	v_pk_fma_f32 v[16:17], v[170:171], v[4:5], v[186:187]
	v_pk_fma_f32 v[14:15], v[168:169], v[2:3], v[184:185]
	global_store_dwordx4 v[28:29], v[14:17], off
	v_pk_mul_f32 v[2:3], v[16:17], v[16:17]
	v_pk_mul_f32 v[4:5], v[14:15], v[14:15]
	s_nop 0
	v_pk_mov_b32 v[8:9], v[4:5], v[2:3] op_sel:[1,0]
	v_mov_b32_e32 v5, v3
	v_pk_add_f32 v[50:51], v[8:9], v[4:5]
	v_lshlrev_b32_e32 v12, 16, v146
	v_and_b32_e32 v13, 0xffff0000, v146
	v_lshlrev_b32_e32 v46, 16, v147
	v_and_b32_e32 v47, 0xffff0000, v147
	v_pk_mul_f32 v[46:47], v[0:1], v[46:47] op_sel_hi:[0,1]
	v_pk_mul_f32 v[12:13], v[0:1], v[12:13] op_sel_hi:[0,1]
	s_waitcnt vmcnt(9)
	v_pk_mul_f32 v[2:3], v[156:157], v[12:13]
	v_pk_mul_f32 v[4:5], v[158:159], v[46:47]
	s_waitcnt vmcnt(7)
	v_pk_fma_f32 v[12:13], v[174:175], v[4:5], v[190:191]
	v_pk_fma_f32 v[10:11], v[172:173], v[2:3], v[188:189]
	global_store_dwordx4 v[28:29], v[10:13], off offset:1024
	v_pk_mul_f32 v[2:3], v[12:13], v[12:13]
	v_pk_mul_f32 v[4:5], v[10:11], v[10:11]
	s_nop 0
	v_pk_mov_b32 v[8:9], v[4:5], v[2:3] op_sel:[1,0]
	v_mov_b32_e32 v5, v3
	v_pk_add_f32 v[52:53], v[8:9], v[4:5]
	v_lshlrev_b32_e32 v8, 16, v148
	v_and_b32_e32 v9, 0xffff0000, v148
	v_lshlrev_b32_e32 v54, 16, v149
	v_and_b32_e32 v55, 0xffff0000, v149
	v_pk_mul_f32 v[54:55], v[0:1], v[54:55] op_sel_hi:[0,1]
	v_pk_mul_f32 v[8:9], v[0:1], v[8:9] op_sel_hi:[0,1]
	s_waitcnt vmcnt(7)
	v_pk_mul_f32 v[2:3], v[160:161], v[8:9]
	v_pk_mul_f32 v[4:5], v[162:163], v[54:55]
	s_waitcnt vmcnt(5)
	v_pk_fma_f32 v[2:3], v[176:177], v[2:3], v[192:193]
	v_pk_fma_f32 v[4:5], v[178:179], v[4:5], v[194:195]
	global_store_dwordx4 v[28:29], v[2:5], off offset:2048
	v_lshlrev_b32_e32 v54, 16, v150
	v_and_b32_e32 v55, 0xffff0000, v150
	v_lshlrev_b32_e32 v56, 16, v151
	v_and_b32_e32 v57, 0xffff0000, v151
	s_nop 0
	v_pk_mul_f32 v[56:57], v[0:1], v[56:57] op_sel_hi:[0,1]
	v_pk_mul_f32 v[54:55], v[0:1], v[54:55] op_sel_hi:[0,1]
	s_waitcnt vmcnt(5)
	v_pk_mul_f32 v[42:43], v[164:165], v[54:55]
	v_pk_mul_f32 v[44:45], v[166:167], v[56:57]
	s_waitcnt vmcnt(3)
; __device__ __forceinline__ unsigned pk2(float lo, float hi) { const f32x2 v = {lo, hi}; const bf16x2_t b = __builtin_convertvector(v, bf16x2_t); return __builtin_bit_cast(unsigned, b); }
; __device__ __forceinline__ float dot4(f32x4 a) { return (a[0] * a[0] + a[1] * a[1]) + (a[2] * a[2] + a[3] * a[3]); }
; __device__ __forceinline__ void ph_x1rows(int tbase) {
;     ...
;             v[j] = *(const f32x4*)(x + (size_t)t * 1024 + c0) + ga * (f * rs1 * g); *(f32x4*)(out + (size_t)t * 1024 + c0) = v[j]; s += dot4(v[j]); }
;         const float rs2 = rsqrtf(wave_sum(s) * (1.f / 1024.f) + EPS);
; #pragma unroll
;         for (int j = 0; j < 4; ++j) { const int c0 = 4 * lane + 256 * j; const f32x4 g = *(const f32x4*)(g_pre_mlp + c0), sc = *(const f32x4*)(mod + 4096 + c0), sh = *(const f32x4*)(mod + 3072 + c0);
;             const f32x4 hv = v[j] * rs2 * g * (sc + 1.f) + sh; u32x2 w; w.x = pk2(hv[0], hv[1]); w.y = pk2(hv[2], hv[3]); *(u32x2*)(H + (size_t)m * 1024 + c0) = w; } }
	v_pk_fma_f32 v[6:7], v[180:181], v[42:43], v[196:197]
	v_pk_fma_f32 v[8:9], v[182:183], v[44:45], v[198:199]
	global_store_dwordx4 v[28:29], v[6:9], off offset:3072
	v_mul_f32_e32 v0, v6, v6
	v_mul_f32_e32 v41, v7, v7
	v_pk_add_f32 v[28:29], v[50:51], v[50:51] op_sel:[0,1] op_sel_hi:[1,0]
	v_pk_add_f32 v[42:43], v[52:53], v[52:53] op_sel:[0,1] op_sel_hi:[1,0]
	v_mov_b32_e32 v29, v0
	v_mov_b32_e32 v43, v41
	v_mul_f32_e32 v0, v3, v3
	v_mul_f32_e32 v44, v8, v8
	v_pk_add_f32 v[28:29], v[28:29], v[42:43]
	v_pk_fma_f32 v[42:43], v[2:3], v[2:3], v[0:1] op_sel_hi:[1,1,0]
	v_mul_f32_e32 v0, v5, v5
	v_mul_f32_e32 v46, v9, v9
	v_mov_b32_e32 v43, v44
	v_pk_fma_f32 v[44:45], v[4:5], v[4:5], v[0:1] op_sel_hi:[1,1,0]
	s_nop 0
	v_mov_b32_e32 v45, v46
	v_pk_add_f32 v[42:43], v[42:43], v[44:45]
	s_nop 0
	v_pk_add_f32 v[28:29], v[28:29], v[42:43]
	global_load_dwordx4 v[42:45], v[18:19], off
	global_load_dwordx4 v[46:49], v37, s[64:65]
	global_load_dwordx4 v[50:53], v37, s[72:73]
	v_add_f32_e32 v0, v28, v29
	ds_bpermute_b32 v28, v30, v0
	s_waitcnt lgkmcnt(0)
	v_add_f32_e32 v0, v0, v28
	ds_bpermute_b32 v28, v31, v0
	s_waitcnt lgkmcnt(0)
	v_add_f32_e32 v0, v0, v28
	ds_bpermute_b32 v28, v32, v0
	s_waitcnt lgkmcnt(0)
	v_add_f32_e32 v0, v0, v28
	ds_bpermute_b32 v28, v33, v0
	s_waitcnt lgkmcnt(0)
	v_add_f32_e32 v0, v0, v28
	ds_bpermute_b32 v28, v34, v0
	s_waitcnt lgkmcnt(0)
	v_add_f32_e32 v0, v0, v28
	ds_bpermute_b32 v28, v35, v0
	s_waitcnt lgkmcnt(0)
	v_add_f32_e32 v0, v0, v28
	v_fmamk_f32 v0, v0, 0x3a800000, v220
	v_cmp_gt_f32_e64 s[38:39], s51, v0
	v_mul_f32_e32 v28, 0x4b800000, v0
	s_nop 0
	v_cndmask_b32_e64 v0, v0, v28, s[38:39]
	v_rsq_f32_e32 v0, v0
	s_nop 0
	v_mul_f32_e32 v28, 0x45800000, v0
	v_cndmask_b32_e64 v0, v0, v28, s[38:39]
	v_pk_mul_f32 v[16:17], v[16:17], v[0:1] op_sel_hi:[1,0]
	v_pk_mul_f32 v[14:15], v[14:15], v[0:1] op_sel_hi:[1,0]
	v_pk_mul_f32 v[12:13], v[12:13], v[0:1] op_sel_hi:[1,0]
	v_pk_mul_f32 v[10:11], v[10:11], v[0:1] op_sel_hi:[1,0]
	v_pk_mul_f32 v[4:5], v[4:5], v[0:1] op_sel_hi:[1,0]
	v_pk_mul_f32 v[2:3], v[2:3], v[0:1] op_sel_hi:[1,0]
	v_pk_mul_f32 v[8:9], v[8:9], v[0:1] op_sel_hi:[1,0]
	v_pk_mul_f32 v[6:7], v[6:7], v[0:1] op_sel_hi:[1,0]
	s_waitcnt vmcnt(2)
	v_pk_mul_f32 v[14:15], v[42:43], v[14:15]
	v_pk_mul_f32 v[16:17], v[44:45], v[16:17]
	s_waitcnt vmcnt(1)
	v_pk_add_f32 v[28:29], v[48:49], 1.0 op_sel_hi:[1,0]
	v_pk_add_f32 v[42:43], v[46:47], 1.0 op_sel_hi:[1,0]
	s_waitcnt vmcnt(0)
	v_pk_fma_f32 v[16:17], v[28:29], v[16:17], v[52:53]
	v_pk_fma_f32 v[14:15], v[42:43], v[14:15], v[50:51]
	s_nop 0
	v_cvt_pk_bf16_f32 v14, v14, v15
	v_cvt_pk_bf16_f32 v15, v16, v17
	v_add_co_u32_e64 v16, s[38:39], s2, v26
	s_mov_b32 s2, 0xe7c01000
	s_nop 0
	v_addc_co_u32_e64 v17, s[38:39], -1, v27, s[38:39]
	global_store_dwordx2 v[16:17], v[14:15], off
	global_load_dwordx4 v[14:17], v[18:19], off offset:1024
	s_nop 0
	global_load_dwordx4 v[42:45], v38, s[64:65]
	global_load_dwordx4 v[46:49], v38, s[72:73]
	v_add_co_u32_e64 v28, s[38:39], s2, v26
	s_waitcnt vmcnt(2)
	v_pk_mul_f32 v[10:11], v[14:15], v[10:11]
	v_pk_mul_f32 v[12:13], v[16:17], v[12:13]
	s_waitcnt vmcnt(1)
	v_pk_add_f32 v[14:15], v[44:45], 1.0 op_sel_hi:[1,0]
	v_pk_add_f32 v[16:17], v[42:43], 1.0 op_sel_hi:[1,0]
	s_waitcnt vmcnt(0)
	v_pk_fma_f32 v[12:13], v[14:15], v[12:13], v[48:49]
	v_pk_fma_f32 v[10:11], v[16:17], v[10:11], v[46:47]
	v_addc_co_u32_e64 v29, s[38:39], -1, v27, s[38:39]
	v_cvt_pk_bf16_f32 v10, v10, v11
	v_cvt_pk_bf16_f32 v11, v12, v13
	global_store_dwordx2 v[28:29], v[10:11], off offset:-3584
	global_load_dwordx4 v[10:13], v[18:19], off offset:2048
	s_nop 0
	global_load_dwordx4 v[14:17], v39, s[64:65]
	global_load_dwordx4 v[42:45], v39, s[72:73]
	v_lshl_add_u64 v[26:27], v[26:27], 0, s[42:43]
	s_waitcnt vmcnt(2)
	v_pk_mul_f32 v[2:3], v[10:11], v[2:3]
	v_pk_mul_f32 v[4:5], v[12:13], v[4:5]
	s_waitcnt vmcnt(1)
	v_pk_add_f32 v[10:11], v[16:17], 1.0 op_sel_hi:[1,0]
	v_pk_add_f32 v[12:13], v[14:15], 1.0 op_sel_hi:[1,0]
	s_waitcnt vmcnt(0)
	v_pk_fma_f32 v[4:5], v[10:11], v[4:5], v[44:45]
	v_pk_fma_f32 v[2:3], v[12:13], v[2:3], v[42:43]
	s_nop 0
	v_cvt_pk_bf16_f32 v2, v2, v3
	v_cvt_pk_bf16_f32 v3, v4, v5
	global_store_dwordx2 v[28:29], v[2:3], off offset:-3072
	global_load_dwordx4 v[2:5], v[18:19], off offset:3072
	s_nop 0
	global_load_dwordx4 v[10:13], v40, s[64:65]
	global_load_dwordx4 v[14:17], v40, s[72:73]
	s_waitcnt vmcnt(2)
	v_pk_mul_f32 v[2:3], v[2:3], v[6:7]
	v_pk_mul_f32 v[4:5], v[4:5], v[8:9]
	s_waitcnt vmcnt(1)
	v_pk_add_f32 v[6:7], v[12:13], 1.0 op_sel_hi:[1,0]
	v_pk_add_f32 v[8:9], v[10:11], 1.0 op_sel_hi:[1,0]
	s_waitcnt vmcnt(0)
	v_pk_fma_f32 v[4:5], v[6:7], v[4:5], v[16:17]
	v_pk_fma_f32 v[2:3], v[8:9], v[2:3], v[14:15]
	s_nop 0
	v_cvt_pk_bf16_f32 v2, v2, v3
	v_cvt_pk_bf16_f32 v3, v4, v5
	global_store_dwordx2 v[28:29], v[2:3], off offset:-2560
	s_cbranch_scc0 .LBB0_1220
